# S5 carry scan: scalar mul/fma/add steps (bit-identical), tail LDS reads issued ahead of the serial chain
# baseline (speedup 1.0000x reference)
; #define LAS __attribute__((address_space(3)))
; __device__ __forceinline__ f32x2 cmul(f32x2 a, f32x2 b) { return (f32x2){a.x * b.x - a.y * b.y, a.x * b.y + a.y * b.x}; }
; __global__ void __launch_bounds__(512, 2) fwd_kernel(Args a) {
;     ...
;                 const f32x2 aT = AT[g * NP + lane]; f32x2 S = (f32x2){0.f, 0.f};
;                 const int ch = lane >> 1, wo = (lane & 1) * 8;
;                 for (int c = 0; c < c0; c += 16) {
;                     f32x2 ev[16];
; #pragma unroll
;                     for (int q = 0; q < 16; ++q) ev[q] = *(const LAS f32x2*)(EbB + (c + q) * 512 + ((ch ^ q) << 4) + wo);
; #pragma unroll
;                     for (int q = 0; q < 16; ++q) S = cmul(aT, S) + ev[q];
;                 }
.LBB0_281:
	v_mul_f32_e32 v26, v4, v8
	v_mul_f32_e32 v27, v5, v9
	v_add_u32_e32 v28, v10, v84
	v_fma_f32 v62, v2, v8, -v27
	v_fma_f32 v63, v3, v9, v26
	v_add_u32_e32 v30, v11, v84
	v_add_u32_e32 v32, v12, v84
	v_add_u32_e32 v36, v13, v84
	v_add_u32_e32 v38, v14, v84
	v_add_u32_e32 v40, v15, v84
	v_add_u32_e32 v42, v16, v84
	v_add_u32_e32 v44, v17, v84
	v_add_u32_e32 v46, v18, v84
	v_add_u32_e32 v48, v19, v84
	v_add_u32_e32 v50, v20, v84
	v_add_u32_e32 v52, v21, v84
	v_add_u32_e32 v54, v22, v84
	v_add_u32_e32 v56, v23, v84
	v_add_u32_e32 v58, v24, v84
	v_add_u32_e32 v60, v25, v84
	ds_read_b64 v[28:29], v28
	ds_read_b64 v[30:31], v30
	ds_read_b64 v[32:33], v32
	ds_read_b64 v[36:37], v36
	ds_read_b64 v[38:39], v38
	ds_read_b64 v[40:41], v40
	ds_read_b64 v[42:43], v42
	ds_read_b64 v[44:45], v44
	ds_read_b64 v[46:47], v46
	ds_read_b64 v[48:49], v48
	ds_read_b64 v[50:51], v50
	ds_read_b64 v[52:53], v52
	ds_read_b64 v[54:55], v54
	ds_read_b64 v[56:57], v56
	ds_read_b64 v[58:59], v58
	ds_read_b64 v[60:61], v60
	s_waitcnt lgkmcnt(14)
	v_add_f32_e32 v8, v62, v28
	v_add_f32_e32 v9, v63, v29
	s_add_i32 s35, s35, 16
	v_mul_f32_e32 v26, v4, v8
	v_mul_f32_e32 v27, v5, v9
	v_add_u32_e32 v25, 0x2000, v25
	v_fma_f32 v28, v2, v8, -v27
	v_fma_f32 v29, v3, v9, v26
	v_add_u32_e32 v24, 0x2000, v24
	v_add_f32_e32 v8, v28, v30
	v_add_f32_e32 v9, v29, v31
	v_add_u32_e32 v23, 0x2000, v23
	v_mul_f32_e32 v26, v4, v8
	v_mul_f32_e32 v27, v5, v9
	v_add_u32_e32 v22, 0x2000, v22
	v_fma_f32 v28, v2, v8, -v27
	v_fma_f32 v29, v3, v9, v26
	v_add_u32_e32 v21, 0x2000, v21
	s_waitcnt lgkmcnt(13)
	v_add_f32_e32 v8, v28, v32
	v_add_f32_e32 v9, v29, v33
	v_add_u32_e32 v20, 0x2000, v20
	v_mul_f32_e32 v26, v4, v8
	v_mul_f32_e32 v27, v5, v9
	v_add_u32_e32 v19, 0x2000, v19
	v_fma_f32 v28, v2, v8, -v27
	v_fma_f32 v29, v3, v9, v26
	v_add_u32_e32 v18, 0x2000, v18
	s_waitcnt lgkmcnt(12)
	v_add_f32_e32 v8, v28, v36
	v_add_f32_e32 v9, v29, v37
	v_add_u32_e32 v17, 0x2000, v17
	v_mul_f32_e32 v26, v4, v8
	v_mul_f32_e32 v27, v5, v9
	v_add_u32_e32 v16, 0x2000, v16
	v_fma_f32 v28, v2, v8, -v27
	v_fma_f32 v29, v3, v9, v26
	v_add_u32_e32 v15, 0x2000, v15
	s_waitcnt lgkmcnt(11)
	v_add_f32_e32 v8, v28, v38
	v_add_f32_e32 v9, v29, v39
	v_add_u32_e32 v14, 0x2000, v14
	v_mul_f32_e32 v26, v4, v8
	v_mul_f32_e32 v27, v5, v9
	v_add_u32_e32 v13, 0x2000, v13
	v_fma_f32 v28, v2, v8, -v27
	v_fma_f32 v29, v3, v9, v26
	v_add_u32_e32 v12, 0x2000, v12
	s_waitcnt lgkmcnt(10)
	v_add_f32_e32 v8, v28, v40
	v_add_f32_e32 v9, v29, v41
	v_add_u32_e32 v11, 0x2000, v11
	v_mul_f32_e32 v26, v4, v8
	v_mul_f32_e32 v27, v5, v9
	v_add_u32_e32 v10, 0x2000, v10
	v_fma_f32 v28, v2, v8, -v27
	v_fma_f32 v29, v3, v9, v26
	s_cmp_ge_u32 s35, s6
	s_waitcnt lgkmcnt(9)
	v_add_f32_e32 v8, v28, v42
	v_add_f32_e32 v9, v29, v43
	s_nop 0
	v_mul_f32_e32 v26, v4, v8
	v_mul_f32_e32 v27, v5, v9
	s_nop 0
	v_fma_f32 v28, v2, v8, -v27
	v_fma_f32 v29, v3, v9, v26
	s_nop 0
	s_waitcnt lgkmcnt(8)
	v_add_f32_e32 v8, v28, v44
	v_add_f32_e32 v9, v29, v45
	s_nop 0
	v_mul_f32_e32 v26, v4, v8
	v_mul_f32_e32 v27, v5, v9
	s_nop 0
	v_fma_f32 v28, v2, v8, -v27
	v_fma_f32 v29, v3, v9, v26
	s_nop 0
	s_waitcnt lgkmcnt(7)
	v_add_f32_e32 v8, v28, v46
	v_add_f32_e32 v9, v29, v47
	s_nop 0
	v_mul_f32_e32 v26, v4, v8
	v_mul_f32_e32 v27, v5, v9
	s_nop 0
	v_fma_f32 v28, v2, v8, -v27
	v_fma_f32 v29, v3, v9, v26
	s_nop 0
	s_waitcnt lgkmcnt(6)
	v_add_f32_e32 v8, v28, v48
	v_add_f32_e32 v9, v29, v49
	s_nop 0
	v_mul_f32_e32 v26, v4, v8
	v_mul_f32_e32 v27, v5, v9
	s_nop 0
	v_fma_f32 v28, v2, v8, -v27
	v_fma_f32 v29, v3, v9, v26
	s_nop 0
	s_waitcnt lgkmcnt(5)
	v_add_f32_e32 v8, v28, v50
	v_add_f32_e32 v9, v29, v51
	s_nop 0
	v_mul_f32_e32 v26, v4, v8
	v_mul_f32_e32 v27, v5, v9
	s_nop 0
	v_fma_f32 v28, v2, v8, -v27
	v_fma_f32 v29, v3, v9, v26
	s_nop 0
	s_waitcnt lgkmcnt(4)
	v_add_f32_e32 v8, v28, v52
	v_add_f32_e32 v9, v29, v53
	s_nop 0
	v_mul_f32_e32 v26, v4, v8
	v_mul_f32_e32 v27, v5, v9
	s_nop 0
	v_fma_f32 v28, v2, v8, -v27
	v_fma_f32 v29, v3, v9, v26
	s_nop 0
	s_waitcnt lgkmcnt(3)
	v_add_f32_e32 v8, v28, v54
	v_add_f32_e32 v9, v29, v55
	s_nop 0
	v_mul_f32_e32 v26, v4, v8
	v_mul_f32_e32 v27, v5, v9
	s_nop 0
	v_fma_f32 v28, v2, v8, -v27
	v_fma_f32 v29, v3, v9, v26
	s_nop 0
	s_waitcnt lgkmcnt(2)
	v_add_f32_e32 v8, v28, v56
	v_add_f32_e32 v9, v29, v57
	s_nop 0
	v_mul_f32_e32 v26, v4, v8
	v_mul_f32_e32 v27, v5, v9
	s_nop 0
	v_fma_f32 v28, v2, v8, -v27
	v_fma_f32 v29, v3, v9, v26
	s_nop 0
	s_waitcnt lgkmcnt(1)
	v_add_f32_e32 v8, v28, v58
	v_add_f32_e32 v9, v29, v59
	s_nop 0
	v_mul_f32_e32 v26, v4, v8
	v_mul_f32_e32 v27, v5, v9
	s_nop 0
	v_fma_f32 v28, v2, v8, -v27
	v_fma_f32 v29, v3, v9, v26
	s_nop 0
	s_waitcnt lgkmcnt(0)
	v_add_f32_e32 v8, v28, v60
	v_add_f32_e32 v9, v29, v61
	s_cbranch_scc0 .LBB0_281
	s_mov_b64 s[52:53], 0

; #define LAS __attribute__((address_space(3)))
; __device__ __forceinline__ unsigned cvt_pk_bf16(float lo, float hi) { unsigned r; asm volatile("v_cvt_pk_bf16_f32 %0, %1, %2" : "=v"(r) : "v"(lo), "v"(hi)); return r; }
; __device__ __forceinline__ f32x2 cmul(f32x2 a, f32x2 b) { return (f32x2){a.x * b.x - a.y * b.y, a.x * b.y + a.y * b.x}; }
; __global__ void __launch_bounds__(512, 2) fwd_kernel(Args a) {
;     ...
; #pragma unroll
;                 for (int cc = 0; cc < 16; ++cc) {
;                     *(LAS unsigned*)(hl + cc * 136 + 2 * lane) = cvt_pk_bf16(S.x, S.y);
;                     const f32x2 e = *(const LAS f32x2*)(EbB + (c0 + cc) * 512 + ((ch ^ cc) << 4) + wo); S = cmul(aT, S) + e;
;                 }
;                 if (wave == 7) { out[O_PRE + (size_t)nb * 2048 + g * NP + lane] = S.x; out[O_PIM + (size_t)nb * 2048 + g * NP + lane] = S.y; }
.LBB0_285:
	s_waitcnt vmcnt(0)
	v_add_u32_e32 v28, v113, v96
	ds_read_b64 v[36:37], v28
	v_add_u32_e32 v28, v113, v98
	ds_read_b64 v[38:39], v28 offset:512
	v_add_u32_e32 v28, v113, v99
	ds_read_b64 v[40:41], v28 offset:1024
	v_add_u32_e32 v28, v113, v100
	ds_read_b64 v[42:43], v28 offset:1536
	v_add_u32_e32 v28, v113, v101
	ds_read_b64 v[44:45], v28 offset:2048
	v_add_u32_e32 v28, v113, v102
	ds_read_b64 v[46:47], v28 offset:2560
	v_add_u32_e32 v28, v113, v103
	ds_read_b64 v[48:49], v28 offset:3072
	v_add_u32_e32 v28, v113, v104
	ds_read_b64 v[50:51], v28 offset:3584
	v_cvt_pk_bf16_f32 v6, v8, v9
	ds_write_b32 v143, v6
	v_mul_f32_e32 v10, v4, v8
	v_mul_f32_e32 v11, v5, v9
	s_and_b64 vcc, exec, s[10:11]
	v_fma_f32 v12, v2, v8, -v11
	v_fma_f32 v13, v3, v9, v10
	s_nop 0
	s_waitcnt lgkmcnt(8)
	v_add_f32_e32 v6, v12, v36
	v_add_f32_e32 v7, v13, v37
	s_nop 0
	v_cvt_pk_bf16_f32 v8, v6, v7
	ds_write_b32 v143, v8 offset:272
	v_mul_f32_e32 v10, v4, v6
	v_mul_f32_e32 v11, v5, v7
	s_nop 0
	v_fma_f32 v12, v2, v6, -v11
	v_fma_f32 v13, v3, v7, v10
	s_nop 0
	s_waitcnt lgkmcnt(8)
	v_add_f32_e32 v6, v12, v38
	v_add_f32_e32 v7, v13, v39
	s_nop 0
	v_cvt_pk_bf16_f32 v8, v6, v7
	ds_write_b32 v143, v8 offset:544
	v_mul_f32_e32 v10, v4, v6
	v_mul_f32_e32 v11, v5, v7
	s_nop 0
	v_fma_f32 v12, v2, v6, -v11
	v_fma_f32 v13, v3, v7, v10
	s_nop 0
	s_waitcnt lgkmcnt(8)
	v_add_f32_e32 v6, v12, v40
	v_add_f32_e32 v7, v13, v41
	s_nop 0
	v_cvt_pk_bf16_f32 v8, v6, v7
	ds_write_b32 v143, v8 offset:816
	v_mul_f32_e32 v10, v4, v6
	v_mul_f32_e32 v11, v5, v7
	s_nop 0
	v_fma_f32 v12, v2, v6, -v11
	v_fma_f32 v13, v3, v7, v10
	s_nop 0
	s_waitcnt lgkmcnt(8)
	v_add_f32_e32 v6, v12, v42
	v_add_f32_e32 v7, v13, v43
	s_nop 0
	v_cvt_pk_bf16_f32 v8, v6, v7
	ds_write_b32 v143, v8 offset:1088
	v_mul_f32_e32 v10, v4, v6
	v_mul_f32_e32 v11, v5, v7
	s_nop 0
	v_fma_f32 v12, v2, v6, -v11
	v_fma_f32 v13, v3, v7, v10
	s_nop 0
	s_waitcnt lgkmcnt(8)
	v_add_f32_e32 v6, v12, v44
	v_add_f32_e32 v7, v13, v45
	s_nop 0
	v_cvt_pk_bf16_f32 v8, v6, v7
	ds_write_b32 v143, v8 offset:1360
	v_mul_f32_e32 v10, v4, v6
	v_mul_f32_e32 v11, v5, v7
	s_nop 0
	v_fma_f32 v12, v2, v6, -v11
	v_fma_f32 v13, v3, v7, v10
	s_nop 0
	s_waitcnt lgkmcnt(8)
	v_add_f32_e32 v6, v12, v46
	v_add_f32_e32 v7, v13, v47
	s_nop 0
	v_cvt_pk_bf16_f32 v8, v6, v7
	ds_write_b32 v143, v8 offset:1632
	v_mul_f32_e32 v10, v4, v6
	v_mul_f32_e32 v11, v5, v7
	s_nop 0
	v_fma_f32 v12, v2, v6, -v11
	v_fma_f32 v13, v3, v7, v10
	s_nop 0
	s_waitcnt lgkmcnt(8)
	v_add_f32_e32 v6, v12, v48
	v_add_f32_e32 v7, v13, v49
	s_nop 0
	v_cvt_pk_bf16_f32 v8, v6, v7
	ds_write_b32 v143, v8 offset:1904
	v_mul_f32_e32 v10, v4, v6
	v_mul_f32_e32 v11, v5, v7
	s_nop 0
	v_fma_f32 v12, v2, v6, -v11
	v_fma_f32 v13, v3, v7, v10
	s_nop 0
	s_waitcnt lgkmcnt(8)
	v_add_f32_e32 v6, v12, v50
	v_add_f32_e32 v7, v13, v51
	v_add_u32_e32 v28, v113, v105
	ds_read_b64 v[52:53], v28 offset:4096
	v_add_u32_e32 v28, v113, v106
	ds_read_b64 v[54:55], v28 offset:4608
	v_add_u32_e32 v28, v113, v107
	ds_read_b64 v[56:57], v28 offset:5120
	v_add_u32_e32 v28, v113, v108
	ds_read_b64 v[58:59], v28 offset:5632
	v_add_u32_e32 v28, v113, v109
	ds_read_b64 v[60:61], v28 offset:6144
	v_add_u32_e32 v28, v113, v110
	ds_read_b64 v[62:63], v28 offset:6656
	v_add_u32_e32 v28, v113, v111
	ds_read_b64 v[64:65], v28 offset:7168
	s_nop 0
	v_cvt_pk_bf16_f32 v8, v6, v7
	ds_write_b32 v143, v8 offset:2176
	v_mul_f32_e32 v10, v4, v6
	v_mul_f32_e32 v11, v5, v7
	s_nop 0
	v_fma_f32 v12, v2, v6, -v11
	v_fma_f32 v13, v3, v7, v10
	s_nop 0
	s_waitcnt lgkmcnt(7)
	v_add_f32_e32 v6, v12, v52
	v_add_f32_e32 v7, v13, v53
	s_nop 0
	v_cvt_pk_bf16_f32 v8, v6, v7
	ds_write_b32 v143, v8 offset:2448
	v_mul_f32_e32 v10, v4, v6
	v_mul_f32_e32 v11, v5, v7
	s_nop 0
	v_fma_f32 v12, v2, v6, -v11
	v_fma_f32 v13, v3, v7, v10
	s_nop 0
	s_waitcnt lgkmcnt(7)
	v_add_f32_e32 v6, v12, v54
	v_add_f32_e32 v7, v13, v55
	s_nop 0
	v_cvt_pk_bf16_f32 v8, v6, v7
	ds_write_b32 v143, v8 offset:2720
	v_mul_f32_e32 v10, v4, v6
	v_mul_f32_e32 v11, v5, v7
	s_nop 0
	v_fma_f32 v12, v2, v6, -v11
	v_fma_f32 v13, v3, v7, v10
	s_nop 0
	s_waitcnt lgkmcnt(7)
	v_add_f32_e32 v6, v12, v56
	v_add_f32_e32 v7, v13, v57
	s_nop 0
	v_cvt_pk_bf16_f32 v8, v6, v7
	ds_write_b32 v143, v8 offset:2992
	v_mul_f32_e32 v10, v4, v6
	v_mul_f32_e32 v11, v5, v7
	s_nop 0
	v_fma_f32 v12, v2, v6, -v11
	v_fma_f32 v13, v3, v7, v10
	s_nop 0
	s_waitcnt lgkmcnt(7)
	v_add_f32_e32 v6, v12, v58
	v_add_f32_e32 v7, v13, v59
	s_nop 0
	v_cvt_pk_bf16_f32 v8, v6, v7
	ds_write_b32 v143, v8 offset:3264
	v_mul_f32_e32 v10, v4, v6
	v_mul_f32_e32 v11, v5, v7
	s_nop 0
	v_fma_f32 v12, v2, v6, -v11
	v_fma_f32 v13, v3, v7, v10
	s_nop 0
	s_waitcnt lgkmcnt(7)
	v_add_f32_e32 v6, v12, v60
	v_add_f32_e32 v7, v13, v61
	s_nop 0
	v_cvt_pk_bf16_f32 v8, v6, v7
	ds_write_b32 v143, v8 offset:3536
	v_mul_f32_e32 v10, v4, v6
	v_mul_f32_e32 v11, v5, v7
	s_nop 0
	v_fma_f32 v12, v2, v6, -v11
	v_fma_f32 v13, v3, v7, v10
	s_nop 0
	s_waitcnt lgkmcnt(7)
	v_add_f32_e32 v6, v12, v62
	v_add_f32_e32 v7, v13, v63
	s_nop 0
	v_cvt_pk_bf16_f32 v8, v6, v7
	ds_write_b32 v143, v8 offset:3808
	v_mul_f32_e32 v10, v4, v6
	v_mul_f32_e32 v11, v5, v7
	s_nop 0
	v_fma_f32 v12, v2, v6, -v11
	v_fma_f32 v13, v3, v7, v10
	s_nop 0
	s_waitcnt lgkmcnt(7)
	v_add_f32_e32 v6, v12, v64
	v_add_f32_e32 v7, v13, v65
	s_nop 0
	v_cvt_pk_bf16_f32 v8, v6, v7
	ds_write_b32 v143, v8 offset:4080
	s_cbranch_vccz .LBB0_278
	s_ashr_i32 s51, s50, 31
	s_lshl_b32 s35, s34, 13
	s_add_u32 s35, s12, s35
	s_addc_u32 s39, s13, 0
	s_lshl_b64 s[36:37], s[50:51], 2
	v_add_u32_e32 v8, v113, v112
	s_add_u32 s36, s35, s36
	ds_read_b64 v[8:9], v8 offset:7680
	v_pk_mul_f32 v[4:5], v[4:5], v[6:7]
	v_mov_b32_e32 v75, v67
	s_addc_u32 s37, s39, s37
	v_pk_fma_f32 v[10:11], v[2:3], v[6:7], v[4:5] op_sel:[0,0,1] op_sel_hi:[1,1,0] neg_lo:[0,0,1] neg_hi:[0,0,1]
	v_pk_fma_f32 v[2:3], v[2:3], v[6:7], v[4:5] op_sel:[0,0,1] op_sel_hi:[1,1,0]
	v_lshl_add_u64 v[4:5], s[36:37], 0, v[74:75]
	v_add_co_u32_e32 v6, vcc, 0x4080000, v4
	v_mov_b32_e32 v11, v3
	s_nop 0
	v_addc_co_u32_e32 v7, vcc, 0, v5, vcc
	v_add_co_u32_e32 v4, vcc, 0x4090000, v4
	s_waitcnt lgkmcnt(0)
	v_pk_add_f32 v[2:3], v[10:11], v[8:9]
	v_addc_co_u32_e32 v5, vcc, 0, v5, vcc
	global_store_dword v[6:7], v2, off
	global_store_dword v[4:5], v3, off
	s_branch .LBB0_278
